# P9: all K/rope fragment reads issued up front in the QK segment; unit-epilogue gate loads hoisted to the unit prologue
# speedup vs baseline: 1.0276x; 1.0025x over previous
.LBB0_1311:
	v_and_b32_e32 v2, 64, v179
	v_xor_b32_e32 v1, 32, v179
	v_add_u32_e32 v2, 64, v2
	v_cmp_lt_i32_e32 vcc, v1, v2
	s_mulk_i32 s41, 0x2200
	s_nop 0
	v_cndmask_b32_e32 v1, v179, v1, vcc
	v_lshlrev_b32_e32 v1, 2, v1
	ds_bpermute_b32 v1, v1, v164
	s_waitcnt lgkmcnt(0)
	v_add_f32_e32 v1, v164, v1
	v_div_scale_f32 v2, s[2:3], v1, v1, 1.0
	v_rcp_f32_e32 v3, v2
	v_div_scale_f32 v4, vcc, 1.0, v1, 1.0
	s_add_i32 s2, s41, 0
	v_fma_f32 v5, -v2, v3, 1.0
	v_fmac_f32_e32 v3, v5, v3
	v_mul_f32_e32 v5, v4, v3
	v_fma_f32 v6, -v2, v5, v4
	v_fmac_f32_e32 v5, v6, v3
	v_fma_f32 v2, -v2, v5, v4
	v_div_fmas_f32 v2, v2, v3, v5
	v_div_fixup_f32 v6, v2, v1, 1.0
	v_mul_u32_u24_e32 v1, 0x110, v162
	v_add3_u32 v1, s2, v1, v144
	v_pk_mul_f32 v[2:3], v[32:33], v[6:7] op_sel_hi:[1,0]
	v_pk_mul_f32 v[4:5], v[34:35], v[6:7] op_sel_hi:[1,0]
	ds_write_b128 v1, v[2:5] offset:49152
	v_pk_mul_f32 v[2:3], v[36:37], v[6:7] op_sel_hi:[1,0]
	v_pk_mul_f32 v[4:5], v[38:39], v[6:7] op_sel_hi:[1,0]
	ds_write_b128 v1, v[2:5] offset:49184
	v_pk_mul_f32 v[2:3], v[40:41], v[6:7] op_sel_hi:[1,0]
	v_pk_mul_f32 v[4:5], v[42:43], v[6:7] op_sel_hi:[1,0]
	ds_write_b128 v1, v[2:5] offset:49216
	v_pk_mul_f32 v[2:3], v[44:45], v[6:7] op_sel_hi:[1,0]
	v_pk_mul_f32 v[4:5], v[46:47], v[6:7] op_sel_hi:[1,0]
	ds_write_b128 v1, v[2:5] offset:49248
	v_pk_mul_f32 v[2:3], v[16:17], v[6:7] op_sel_hi:[1,0]
	v_pk_mul_f32 v[4:5], v[18:19], v[6:7] op_sel_hi:[1,0]
	ds_write_b128 v1, v[2:5] offset:49280
	v_pk_mul_f32 v[2:3], v[20:21], v[6:7] op_sel_hi:[1,0]
	v_pk_mul_f32 v[4:5], v[22:23], v[6:7] op_sel_hi:[1,0]
	ds_write_b128 v1, v[2:5] offset:49312
	v_pk_mul_f32 v[2:3], v[24:25], v[6:7] op_sel_hi:[1,0]
	v_pk_mul_f32 v[4:5], v[26:27], v[6:7] op_sel_hi:[1,0]
	s_ashr_i32 s41, s40, 31
	ds_write_b128 v1, v[2:5] offset:49344
	v_pk_mul_f32 v[2:3], v[28:29], v[6:7] op_sel_hi:[1,0]
	v_pk_mul_f32 v[4:5], v[30:31], v[6:7] op_sel_hi:[1,0]
	s_lshl_b64 s[4:5], s[40:41], 10
	ds_write_b128 v1, v[2:5] offset:49376
	v_lshl_or_b32 v1, v161, 3, s4
	v_mov_b32_e32 v3, s5
	v_or_b32_e32 v2, s34, v1
	v_lshrrev_b32_e32 v16, 3, v0
	v_lshlrev_b64 v[12:13], 1, v[2:3]
	v_lshl_add_u64 v[14:15], s[10:11], 0, v[12:13]
	v_lshlrev_b32_e32 v144, 11, v16
	s_waitcnt lgkmcnt(0)
	v_lshl_add_u64 v[0:1], v[14:15], 0, v[144:145]
	s_nop 0
	v_or_b32_e32 v32, 0x4000, v144
	v_mov_b32_e32 v33, v145
	v_lshl_add_u64 v[4:5], v[14:15], 0, v[32:33]
	s_nop 0
	v_or_b32_e32 v34, 0x8000, v144
	v_mov_b32_e32 v35, v145
	v_lshl_add_u64 v[8:9], v[14:15], 0, v[34:35]
	s_nop 0
	v_lshl_add_u64 v[36:37], s[14:15], 0, v[12:13]
	v_lshl_add_u64 v[38:39], v[36:37], 0, v[144:145]
	v_or_b32_e32 v144, 0xc000, v144
	v_lshl_add_u64 v[12:13], v[14:15], 0, v[144:145]
	s_nop 0
	v_lshlrev_b32_e32 v17, 5, v161
	v_mul_u32_u24_e32 v16, 0x110, v16
	v_add3_u32 v48, s2, v17, v16
	ds_read_b128 v[16:19], v48 offset:49152
	ds_read_b128 v[20:23], v48 offset:49168
	ds_read_b128 v[24:27], v48 offset:51328
	ds_read_b128 v[28:31], v48 offset:51344
	s_waitcnt vmcnt(0)
	v_lshlrev_b32_e32 v40, 16, v146
	v_and_b32_e32 v41, 0xffff0000, v146
	v_lshlrev_b32_e32 v0, 16, v147
	v_and_b32_e32 v1, 0xffff0000, v147
	v_lshlrev_b32_e32 v42, 16, v148
	v_and_b32_e32 v43, 0xffff0000, v148
	v_lshlrev_b32_e32 v2, 16, v149
	v_and_b32_e32 v3, 0xffff0000, v149
	s_waitcnt lgkmcnt(3)
	v_pk_mul_f32 v[16:17], v[16:17], v[40:41]
	v_pk_mul_f32 v[18:19], v[18:19], v[0:1]
	s_waitcnt lgkmcnt(2)
	v_pk_mul_f32 v[20:21], v[20:21], v[42:43]
	v_pk_mul_f32 v[22:23], v[22:23], v[2:3]
	v_cvt_pk_bf16_f32 v0, v16, v17
	v_cvt_pk_bf16_f32 v1, v18, v19
	v_cvt_pk_bf16_f32 v2, v20, v21
	v_cvt_pk_bf16_f32 v3, v22, v23
	global_store_dwordx4 v[38:39], v[0:3], off
	s_nop 0
	v_lshlrev_b32_e32 v44, 16, v150
	v_and_b32_e32 v45, 0xffff0000, v150
	v_lshlrev_b32_e32 v0, 16, v153
	v_and_b32_e32 v1, 0xffff0000, v153
	v_lshlrev_b32_e32 v4, 16, v151
	v_and_b32_e32 v5, 0xffff0000, v151
	v_lshlrev_b32_e32 v46, 16, v152
	v_and_b32_e32 v47, 0xffff0000, v152
	s_waitcnt lgkmcnt(0)
	v_pk_mul_f32 v[0:1], v[30:31], v[0:1]
	v_pk_mul_f32 v[24:25], v[24:25], v[44:45]
	v_pk_mul_f32 v[26:27], v[26:27], v[4:5]
	v_pk_mul_f32 v[28:29], v[28:29], v[46:47]
	v_cvt_pk_bf16_f32 v7, v0, v1
	ds_read_b128 v[0:3], v48 offset:53504
	v_cvt_pk_bf16_f32 v4, v24, v25
	v_cvt_pk_bf16_f32 v5, v26, v27
	v_cvt_pk_bf16_f32 v6, v28, v29
	v_lshl_add_u64 v[16:17], v[36:37], 0, v[32:33]
	global_store_dwordx4 v[16:17], v[4:7], off
	ds_read_b128 v[4:7], v48 offset:53520
	s_nop 0
	v_lshlrev_b32_e32 v16, 16, v166
	v_and_b32_e32 v17, 0xffff0000, v166
	v_lshlrev_b32_e32 v8, 16, v167
	v_and_b32_e32 v9, 0xffff0000, v167
	s_waitcnt lgkmcnt(1)
	v_pk_mul_f32 v[0:1], v[0:1], v[16:17]
	v_pk_mul_f32 v[2:3], v[2:3], v[8:9]
	v_cvt_pk_bf16_f32 v0, v0, v1
	v_cvt_pk_bf16_f32 v1, v2, v3
	v_lshlrev_b32_e32 v2, 16, v168
	v_and_b32_e32 v3, 0xffff0000, v168
	s_waitcnt lgkmcnt(0)
	v_pk_mul_f32 v[2:3], v[4:5], v[2:3]
	v_lshlrev_b32_e32 v4, 16, v169
	v_and_b32_e32 v5, 0xffff0000, v169
	v_pk_mul_f32 v[4:5], v[6:7], v[4:5]
	v_cvt_pk_bf16_f32 v2, v2, v3
	v_cvt_pk_bf16_f32 v3, v4, v5
	ds_read_b128 v[4:7], v48 offset:55680
	v_lshl_add_u64 v[8:9], v[36:37], 0, v[34:35]
	global_store_dwordx4 v[8:9], v[0:3], off
	ds_read_b128 v[0:3], v48 offset:55696
	s_nop 0
	v_lshlrev_b32_e32 v8, 16, v250
	v_and_b32_e32 v9, 0xffff0000, v250
	s_waitcnt lgkmcnt(1)
	v_pk_mul_f32 v[4:5], v[4:5], v[8:9]
	v_lshlrev_b32_e32 v8, 16, v251
	v_and_b32_e32 v9, 0xffff0000, v251
	v_pk_mul_f32 v[6:7], v[6:7], v[8:9]
	v_cvt_pk_bf16_f32 v4, v4, v5
	v_cvt_pk_bf16_f32 v5, v6, v7
	v_lshlrev_b32_e32 v6, 16, v252
	v_and_b32_e32 v7, 0xffff0000, v252
	s_waitcnt lgkmcnt(0)
	v_pk_mul_f32 v[0:1], v[0:1], v[6:7]
	s_nop 0
	v_cvt_pk_bf16_f32 v6, v0, v1
	v_lshlrev_b32_e32 v0, 16, v253
	v_and_b32_e32 v1, 0xffff0000, v253
	v_pk_mul_f32 v[0:1], v[2:3], v[0:1]
	s_nop 0
	v_cvt_pk_bf16_f32 v7, v0, v1
	v_lshl_add_u64 v[0:1], v[36:37], 0, v[144:145]
	global_store_dwordx4 v[0:1], v[4:7], off
	s_waitcnt lgkmcnt(0)

.Lp9m_pro_done:
	s_lshl_b32 s89, s40, 11
	s_add_u32 s90, s10, s89
	s_addc_u32 s91, s11, 0
	v_lshl_or_b32 v249, v161, 3, s34
	v_bfe_u32 v254, v163, 3, 3
	v_lshlrev_b32_e32 v249, 1, v249
	v_lshl_add_u32 v249, v254, 11, v249
	global_load_dwordx4 v[146:149], v249, s[90:91]
	s_add_u32 s90, s90, 0x4000
	s_addc_u32 s91, s91, 0
	global_load_dwordx4 v[150:153], v249, s[90:91]
	s_add_u32 s90, s90, 0x4000
	s_addc_u32 s91, s91, 0
	global_load_dwordx4 v[166:169], v249, s[90:91]
	s_add_u32 s90, s90, 0x4000
	s_addc_u32 s91, s91, 0
	global_load_dwordx4 v[250:253], v249, s[90:91]
	s_add_i32 s50, s76, 4
	s_cmp_lt_i32 s50, 1
	s_waitcnt lgkmcnt(0)
	s_barrier
	s_cbranch_scc1 .LBB0_1369
	s_add_i32 s51, s77, s76
	s_add_u32 s46, s46, 0xc201000
	s_addc_u32 s47, s47, 0
	v_add_u32_e32 v22, v19, v20
	v_mov_b32_e32 v23, v145
	s_or_b32 s4, s4, s78
	v_lshl_add_u64 v[154:155], s[46:47], 0, v[22:23]
	s_add_u32 s46, s4, 0x23b20000
	v_mov_b32_e32 v17, v145
	s_addc_u32 s47, s5, 0
	v_lshl_add_u64 v[156:157], s[46:47], 0, v[16:17]
	v_lshlrev_b32_e32 v16, 9, v163
	v_and_b32_e32 v16, 0x18000, v16
	v_lshlrev_b32_e32 v17, 13, v18
	v_or3_b32 v16, v16, v17, v21
	v_mov_b32_e32 v17, v145
	v_mov_b32_e32 v30, v145
	v_mov_b32_e32 v31, v145
	v_lshl_add_u64 v[158:159], s[4:5], 0, v[16:17]
	v_mov_b32_e32 v16, v145
	v_mov_b32_e32 v18, v145
	v_mov_b32_e32 v19, v145
	v_mov_b32_e32 v20, v145
	v_mov_b32_e32 v21, v145
	v_mov_b32_e32 v22, v145
	v_mov_b32_e32 v24, v145
	v_mov_b32_e32 v25, v145
	v_mov_b32_e32 v26, v145
	v_mov_b32_e32 v27, v145
	v_mov_b32_e32 v28, v145
	v_mov_b32_e32 v29, v145
	v_mov_b64_e32 v[46:47], v[30:31]
	v_mul_u32_u24_e32 v173, 0x90, v162
	v_mul_u32_u24_e32 v171, 0x50, v162
	s_add_i32 s52, s76, 3
	s_mov_b32 s54, 0
	s_mov_b64 s[4:5], -1
	v_mov_b32_e32 v164, 0
	v_mov_b32_e32 v165, 0
	v_mov_b64_e32 v[44:45], v[28:29]
	v_mov_b64_e32 v[42:43], v[26:27]
	v_mov_b64_e32 v[40:41], v[24:25]
	v_mov_b64_e32 v[38:39], v[22:23]
	v_mov_b64_e32 v[36:37], v[20:21]
	v_mov_b64_e32 v[34:35], v[18:19]
	v_mov_b64_e32 v[32:33], v[16:17]

.LBB0_1341:
	s_cmp_gt_i32 s54, s51
	s_cselect_b64 s[48:49], -1, 0
	s_or_b64 s[48:49], s[44:45], s[48:49]
	s_and_b64 vcc, exec, s[48:49]
	s_cbranch_vccnz .LBB0_1350
	s_xor_b64 s[48:49], s[4:5], -1
	s_bitcmp1_b32 s54, 0
	s_cselect_b32 s4, 0x5c00, 0
	s_add_i32 s4, s4, 0
	v_add3_u32 v160, s4, v173, v144
	v_add3_u32 v248, s4, v171, v144
	ds_read_b128 v[48:51], v160
	ds_read_b128 v[124:127], v160 offset:4608
	ds_read_b128 v[112:115], v160 offset:32
	ds_read_b128 v[128:131], v160 offset:4640
	ds_read_b128 v[116:119], v160 offset:64
	ds_read_b128 v[132:135], v160 offset:4672
	ds_read_b128 v[120:123], v160 offset:96
	ds_read_b128 v[136:139], v160 offset:4704
	ds_read_b128 v[194:197], v248 offset:18432
	ds_read_b128 v[202:205], v248 offset:20992
	ds_read_b128 v[198:201], v248 offset:18464
	ds_read_b128 v[206:209], v248 offset:21024
	s_waitcnt lgkmcnt(11)
	v_mfma_f32_32x32x16_bf16 v[64:79], v[48:51], v[100:103], v[0:15]
	s_waitcnt lgkmcnt(10)
	v_mfma_f32_32x32x16_bf16 v[48:63], v[124:127], v[100:103], v[0:15]
	s_waitcnt lgkmcnt(9)
	v_mfma_f32_32x32x16_bf16 v[64:79], v[112:115], v[96:99], v[64:79]
	s_waitcnt lgkmcnt(8)
	v_mfma_f32_32x32x16_bf16 v[48:63], v[128:131], v[96:99], v[48:63]
	s_waitcnt lgkmcnt(7)
	v_mfma_f32_32x32x16_bf16 v[64:79], v[116:119], v[92:95], v[64:79]
	s_waitcnt lgkmcnt(6)
	v_mfma_f32_32x32x16_bf16 v[48:63], v[132:135], v[92:95], v[48:63]
	s_waitcnt lgkmcnt(5)
	v_mfma_f32_32x32x16_bf16 v[64:79], v[120:123], v[88:91], v[64:79]
	s_waitcnt lgkmcnt(4)
	v_mfma_f32_32x32x16_bf16 v[48:63], v[136:139], v[88:91], v[48:63]
	ds_read_b128 v[140:143], v160 offset:9216
	ds_read_b128 v[132:135], v160 offset:9248
	ds_read_b128 v[124:127], v160 offset:9280
	ds_read_b128 v[116:119], v160 offset:9312
	ds_read_b128 v[136:139], v160 offset:13824
	ds_read_b128 v[128:131], v160 offset:13856
	ds_read_b128 v[120:123], v160 offset:13888
	ds_read_b128 v[112:115], v160 offset:13920
	s_waitcnt lgkmcnt(11)
	v_mfma_f32_32x32x16_bf16 v[64:79], v[194:197], v[84:87], v[64:79]
	s_waitcnt lgkmcnt(10)
	v_mfma_f32_32x32x16_bf16 v[48:63], v[202:205], v[84:87], v[48:63]
	s_waitcnt lgkmcnt(9)
	v_mfma_f32_32x32x16_bf16 v[64:79], v[198:201], v[80:83], v[64:79]
	s_waitcnt lgkmcnt(8)
	v_mfma_f32_32x32x16_bf16 v[48:63], v[206:209], v[80:83], v[48:63]
	s_nop 1
	v_max_f32_e32 v160, v65, v65
	v_max_f32_e32 v174, v64, v64
	v_max_f32_e32 v160, v174, v160
	v_max3_f32 v160, v160, v66, v67
	v_max3_f32 v160, v160, v68, v69
	v_max3_f32 v160, v160, v70, v71
	v_max3_f32 v160, v160, v72, v73
	v_max3_f32 v160, v160, v74, v75
	v_max3_f32 v160, v160, v76, v77
	v_max3_f32 v160, v160, v78, v79
	v_max3_f32 v160, v160, v48, v49
	v_max3_f32 v160, v160, v50, v51
	v_max3_f32 v160, v160, v52, v53
	v_max3_f32 v160, v160, v54, v55
	v_max3_f32 v160, v160, v56, v57
	v_max3_f32 v160, v160, v58, v59
	v_max3_f32 v160, v160, v60, v61
	v_max3_f32 v160, v160, v62, v63
	v_mov_b32_e32 v174, v160
	s_nop 1
	v_permlane32_swap_b32_e32 v174, v160
	s_andn2_b64 vcc, exec, s[48:49]
	v_max_f32_e32 v160, v160, v174
	v_cndmask_b32_e64 v174, 0, 1, s[48:49]
	v_cmp_ne_u32_e64 s[4:5], 1, v174
	s_mov_b64 s[48:49], -1
	s_cbranch_vccnz .LBB0_1345
	v_cmp_lt_f32_e32 vcc, s72, v160
	s_cbranch_vccz .LBB0_1358
	v_max_f32_e32 v160, v160, v160
	v_max_f32_e32 v160, 0, v160
